# global attention loop: K/V staging waits relaxed to the two-tile-old loads (vmcnt(3)/(2)) with strict tail
# baseline (speedup 1.0000x reference)
; DI void attn_item(const Params& p, int layer, int item, char* smem) {
;     ...
;       const char* sK = smem + bufsel * KV_B;
;       const char* sV = sK + KT_B;
;       f32x16 S[2];
; #pragma unroll
;       for (int kt = 0; kt < 2; ++kt) {
; #pragma unroll
;         for (int s = 0; s < 4; ++s) {
;           bf16x8 kf = *(const bf16x8*)(sK + (kt * 32 + l32) * KROW + s * 32 + h * 16);
;           S[kt] = MFMA32(kf, qf[s], s == 0 ? cinit : S[kt]);
;         }
;       }
;       if (tile < 64 && maskmode == 1) {
;         int qr = tq >> 6, qc = tq & 63;
;         int ws = min(max(qc - 8, 0), 48);
;         int dr = tile - qr + 7;
; #pragma unroll
;         for (int kt = 0; kt < 2; ++kt)
; #pragma unroll
;           for (int r = 0; r < 16; ++r) {
;             int kc = kt * 32 + crow(r, h);
;             bool ok = (unsigned)(kc - ws) < 16u;
;             int bi = ok ? (dr * 31 + kc - qc + 15) : 0;
;             float bv = s_rpb[bi];
;             S[kt][r] = ok ? (S[kt][r] + bv) : -INFINITY;
;           }
;       } else if (tile < 64 && maskmode == 2) {
; #pragma unroll
;         for (int kt = 0; kt < 2; ++kt)
; #pragma unroll
;           for (int r = 0; r < 16; ++r) {
;             int tk = tile * 64 + kt * 32 + crow(r, h);
;             int dd = tq - tk;
;             bool ok = (dd <= 128) && (dd >= -128);
;             S[kt][r] = ok ? S[kt][r] : -INFINITY;
;           }
;       }
; #pragma unroll
;       for (int r = 0; r < 16; ++r) {
;         S[0][r] = __builtin_amdgcn_exp2f(S[0][r]);
;         S[1][r] = __builtin_amdgcn_exp2f(S[1][r]);
;       }
; #pragma unroll
;       for (int kt = 0; kt < 2; ++kt)
; #pragma unroll
;         for (int s2 = 0; s2 < 2; ++s2) {
;           uint4 pw;
;           pw.x = pack_bf16(S[kt][8 * s2 + 0], S[kt][8 * s2 + 1]);
;           pw.y = pack_bf16(S[kt][8 * s2 + 2], S[kt][8 * s2 + 3]);
;     ...
;   for (int it = 0; it < n_it; it += 2) {
;     if (it + 1 < n_it) { ASWRITE(kb0, vb0, 1); }
;     if (it + 3 < n_it) { AGLOAD(kb0, vb0, TILE_OF(it + 3)); }
;     __builtin_amdgcn_sched_barrier(0);
;     compute(0, TILE_OF(it));
;     __syncthreads();
;     if (it + 1 < n_it) {
;       if (it + 2 < n_it) { ASWRITE(ka0, va0, 0); }
;       if (it + 4 < n_it) { AGLOAD(ka0, va0, TILE_OF(it + 4)); }
;       __builtin_amdgcn_sched_barrier(0);
;       compute(1, TILE_OF(it + 1));
;       __syncthreads();
;     }
;   }
.LBB0_261:
	s_cmp_gt_u32 s2, 65
	v_lshl_add_u64 v[132:133], v[136:137], 0, v[0:1]
	v_lshl_add_u64 v[130:131], v[138:139], 0, v[0:1]
	s_cbranch_scc1 .Lattn0_strictA
	s_waitcnt vmcnt(3)
	ds_write_b128 v135, v[114:117] offset:18432
	s_waitcnt vmcnt(2)
	ds_write2_b64 v143, v[118:119], v[120:121] offset0:128 offset1:130
	s_branch .Lattn0_doneA
.Lattn0_strictA:
	s_waitcnt vmcnt(1)
	ds_write_b128 v135, v[114:117] offset:18432
	s_waitcnt vmcnt(0)
	ds_write2_b64 v143, v[118:119], v[120:121] offset0:128 offset1:130
.Lattn0_doneA:
	s_cmp_gt_u32 s2, 64
	s_cbranch_scc1 .LBB0_263
	v_add_co_u32_e32 v66, vcc, 0x2000, v132
	s_nop 1
	v_addc_co_u32_e32 v67, vcc, 0, v133, vcc
	global_load_dwordx4 v[114:117], v[66:67], off
	global_load_dwordx4 v[118:121], v[130:131], off offset:128
.LBB0_263:
	ds_read_b128 v[82:85], v144
	ds_read_b128 v[86:89], v144 offset:32
	s_cmpk_gt_u32 s2, 0x41
	s_cselect_b64 s[0:1], -1, 0
	s_and_b64 vcc, exec, s[0:1]
	s_waitcnt lgkmcnt(1)
	v_mfma_f32_32x32x16_bf16 v[66:81], v[82:85], v[98:101], v[2:17]
	ds_read_b128 v[82:85], v144 offset:64
	ds_read_b128 v[146:149], v144 offset:4608
	s_waitcnt lgkmcnt(2)
	v_mfma_f32_32x32x16_bf16 v[66:81], v[86:89], v[102:105], v[66:81]
	s_waitcnt lgkmcnt(1)
	v_mfma_f32_32x32x16_bf16 v[66:81], v[82:85], v[106:109], v[66:81]
	ds_read_b128 v[82:85], v144 offset:96
	s_waitcnt lgkmcnt(0)
	v_mfma_f32_32x32x16_bf16 v[66:81], v[82:85], v[110:113], v[66:81]
	v_mfma_f32_32x32x16_bf16 v[82:97], v[146:149], v[98:101], v[2:17]
	ds_read_b128 v[146:149], v144 offset:4640
	s_nop 9
	v_exp_f32_e32 v66, v66
	v_exp_f32_e32 v67, v67
	v_exp_f32_e32 v68, v68
	v_exp_f32_e32 v69, v69
	v_exp_f32_e32 v70, v70
	v_exp_f32_e32 v71, v71
	s_waitcnt lgkmcnt(0)
	v_mfma_f32_32x32x16_bf16 v[82:97], v[146:149], v[102:105], v[82:97]
	ds_read_b128 v[146:149], v144 offset:4672
	v_exp_f32_e32 v72, v72
	v_exp_f32_e32 v73, v73
	v_exp_f32_e32 v145, v74
	v_add_f32_e32 v51, v51, v66
	v_add_f32_e32 v52, v52, v67
	v_add_f32_e32 v51, v51, v68
	v_add_f32_e32 v52, v52, v69
	v_cvt_pk_bf16_f32 v66, v66, v67
	v_cvt_pk_bf16_f32 v67, v68, v69
	s_waitcnt lgkmcnt(0)
	v_mfma_f32_32x32x16_bf16 v[82:97], v[146:149], v[106:109], v[82:97]
	ds_read_b128 v[146:149], v144 offset:4704
	v_add_f32_e32 v51, v51, v70
	v_add_f32_e32 v52, v52, v71
	v_cvt_pk_bf16_f32 v68, v70, v71
	v_add_f32_e32 v51, v51, v72
	v_add_f32_e32 v52, v52, v73
	v_cvt_pk_bf16_f32 v69, v72, v73
	v_exp_f32_e32 v150, v79
	v_exp_f32_e32 v151, v80
	s_waitcnt lgkmcnt(0)
	v_mfma_f32_32x32x16_bf16 v[82:97], v[146:149], v[110:113], v[82:97]
	v_exp_f32_e32 v152, v81
	v_exp_f32_e32 v146, v75
	v_exp_f32_e32 v147, v76
	v_exp_f32_e32 v148, v77
	v_exp_f32_e32 v149, v78
	ds_read_b128 v[70:73], v142 offset:9216
	ds_read_b128 v[74:77], v142 offset:9248
	ds_read_b128 v[78:81], v142 offset:13824
	v_add_f32_e32 v51, v51, v145
	v_add_f32_e32 v52, v52, v150
	v_add_f32_e32 v51, v51, v151
	v_add_f32_e32 v52, v52, v152
	v_exp_f32_e32 v82, v82
	s_waitcnt lgkmcnt(2)
	v_mfma_f32_32x32x16_bf16 v[34:49], v[70:73], v[66:69], v[34:49]
	v_exp_f32_e32 v83, v83
	v_exp_f32_e32 v84, v84
	v_exp_f32_e32 v85, v85
	v_add_f32_e32 v51, v51, v146
	v_add_f32_e32 v52, v52, v147
	v_add_f32_e32 v51, v51, v148
	v_add_f32_e32 v52, v52, v149
	v_exp_f32_e32 v86, v86
	v_exp_f32_e32 v87, v87
	v_exp_f32_e32 v88, v88
	v_exp_f32_e32 v89, v89
	s_waitcnt lgkmcnt(0)
	v_mfma_f32_32x32x16_bf16 v[18:33], v[78:81], v[66:69], v[18:33]
	v_cvt_pk_bf16_f32 v66, v145, v146
	v_cvt_pk_bf16_f32 v67, v147, v148
	v_cvt_pk_bf16_f32 v68, v149, v150
	v_cvt_pk_bf16_f32 v69, v151, v152
	v_exp_f32_e32 v90, v90
	v_exp_f32_e32 v91, v91
	v_exp_f32_e32 v92, v92
	v_mfma_f32_32x32x16_bf16 v[34:49], v[74:77], v[66:69], v[34:49]
	ds_read_b128 v[74:77], v142 offset:13856
	v_exp_f32_e32 v93, v93
	v_exp_f32_e32 v94, v94
	v_exp_f32_e32 v95, v95
	v_exp_f32_e32 v96, v96
	v_exp_f32_e32 v97, v97
	v_add_f32_e32 v51, v51, v82
	v_add_f32_e32 v52, v52, v83
	s_waitcnt lgkmcnt(0)
	v_mfma_f32_32x32x16_bf16 v[18:33], v[74:77], v[66:69], v[18:33]
	ds_read_b128 v[74:77], v142 offset:9280
	v_add_f32_e32 v51, v51, v84
	v_add_f32_e32 v52, v52, v85
	v_add_f32_e32 v51, v51, v86
	v_add_f32_e32 v52, v52, v87
	v_cvt_pk_bf16_f32 v66, v82, v83
	v_cvt_pk_bf16_f32 v67, v84, v85
	v_cvt_pk_bf16_f32 v68, v86, v87
	v_cvt_pk_bf16_f32 v69, v88, v89
	s_waitcnt lgkmcnt(0)
	s_nop 0
	v_mfma_f32_32x32x16_bf16 v[34:49], v[74:77], v[66:69], v[34:49]
	ds_read_b128 v[74:77], v142 offset:13888
	v_add_f32_e32 v51, v51, v88
	v_add_f32_e32 v52, v52, v89
	v_add_f32_e32 v51, v51, v90
	v_add_f32_e32 v52, v52, v91
	s_waitcnt lgkmcnt(0)
	v_mfma_f32_32x32x16_bf16 v[18:33], v[74:77], v[66:69], v[18:33]
	v_cvt_pk_bf16_f32 v66, v90, v91
	v_cvt_pk_bf16_f32 v67, v92, v93
	v_cvt_pk_bf16_f32 v68, v94, v95
	v_cvt_pk_bf16_f32 v69, v96, v97
	ds_read_b128 v[74:77], v142 offset:9312
	ds_read_b128 v[70:73], v142 offset:13920
	v_add_f32_e32 v51, v51, v92
	v_add_f32_e32 v52, v52, v93
	v_add_f32_e32 v51, v51, v94
	v_add_f32_e32 v52, v52, v95
	v_add_f32_e32 v51, v51, v96
	v_add_f32_e32 v52, v52, v97
	s_waitcnt lgkmcnt(0)
	s_barrier
	v_mfma_f32_32x32x16_bf16 v[34:49], v[74:77], v[66:69], v[34:49]
	v_mfma_f32_32x32x16_bf16 v[18:33], v[70:73], v[66:69], v[18:33]
	s_cbranch_vccnz .LBB0_265
	s_cmp_gt_u32 s2, 64
	s_cbranch_scc1 .Lattn0_strictB
	s_waitcnt vmcnt(3)
	ds_write_b128 v135, v[122:125]
	s_waitcnt vmcnt(2)
	ds_write2_b64 v141, v[126:127], v[128:129] offset0:128 offset1:130
	s_branch .LBB0_265
.Lattn0_strictB:
	s_waitcnt vmcnt(1)
	ds_write_b128 v135, v[122:125]
	s_waitcnt vmcnt(0)
	ds_write2_b64 v141, v[126:127], v[128:129] offset0:128 offset1:130
